# P9 residual epilogue: counted vmcnt waits at first use + consumers sunk behind the load cluster (on top of the same for the P8 epilogues)
# baseline (speedup 1.0000x reference)
.LBB0_764:
	s_lshl_b32 s15, s22, 8
	v_mbcnt_lo_u32_b32 v141, -1, 0
	v_mbcnt_hi_u32_b32 v141, -1, v141
	s_add_i32 s15, s15, s38
	v_and_or_b32 v140, v141, 15, s15
	s_lshl_b32 s15, s43, 8
	v_ashrrev_i32_e32 v141, 1, v141
	v_and_b32_e32 v141, -8, v141
	s_or_b32 s15, s15, s39
	v_add_u32_e32 v144, s15, v141
	v_ashrrev_i32_e32 v141, 31, v140
	v_lshlrev_b64 v[140:141], 12, v[140:141]
	v_lshl_add_u64 v[140:141], s[10:11], 0, v[140:141]
	v_ashrrev_i32_e32 v145, 31, v144
	v_lshl_add_u64 v[140:141], v[144:145], 2, v[140:141]
	v_add_co_u32_e32 v208, vcc, s94, v140
	global_load_dwordx4 v[144:147], v[140:141], off
	global_load_dwordx4 v[148:151], v[140:141], off offset:16
	global_load_dwordx4 v[152:155], v[140:141], off offset:512
	global_load_dwordx4 v[156:159], v[140:141], off offset:528
	v_addc_co_u32_e32 v209, vcc, 0, v141, vcc
	v_add_co_u32_e32 v210, vcc, s0, v140
	global_load_dwordx4 v[160:163], v[208:209], off
	global_load_dwordx4 v[164:167], v[208:209], off offset:16
	global_load_dwordx4 v[168:171], v[208:209], off offset:512
	global_load_dwordx4 v[172:175], v[208:209], off offset:528
	v_addc_co_u32_e32 v211, vcc, 0, v141, vcc
	v_add_co_u32_e32 v212, vcc, s1, v140
	global_load_dwordx4 v[176:179], v[210:211], off
	global_load_dwordx4 v[180:183], v[210:211], off offset:16
	global_load_dwordx4 v[184:187], v[210:211], off offset:512
	global_load_dwordx4 v[188:191], v[210:211], off offset:528
	v_addc_co_u32_e32 v213, vcc, 0, v141, vcc
	global_load_dwordx4 v[192:195], v[212:213], off
	global_load_dwordx4 v[196:199], v[212:213], off offset:16
	global_load_dwordx4 v[200:203], v[212:213], off offset:512
	global_load_dwordx4 v[204:207], v[212:213], off offset:528
	s_mov_b64 s[24:25], 0x80000
	s_waitcnt lgkmcnt(0)
	s_waitcnt vmcnt(15)
	v_pk_add_f32 v[126:127], v[126:127], v[146:147]
	v_pk_add_f32 v[124:125], v[124:125], v[144:145]
	s_waitcnt vmcnt(14)
	v_pk_add_f32 v[122:123], v[122:123], v[150:151]
	s_waitcnt vmcnt(12)
	v_pk_add_f32 v[98:99], v[98:99], v[158:159]
	v_pk_add_f32 v[96:97], v[96:97], v[156:157]
	v_pk_add_f32 v[120:121], v[120:121], v[148:149]
	v_pk_add_f32 v[106:107], v[106:107], v[154:155]
	v_pk_add_f32 v[104:105], v[104:105], v[152:153]
	global_store_dwordx4 v[140:141], v[124:127], off
	global_store_dwordx4 v[140:141], v[120:123], off offset:16
	global_store_dwordx4 v[140:141], v[104:107], off offset:512
	global_store_dwordx4 v[140:141], v[96:99], off offset:528
	s_waitcnt vmcnt(13)
	v_pk_add_f32 v[90:91], v[90:91], v[170:171]
	v_pk_add_f32 v[106:107], v[114:115], v[166:167]
	v_pk_add_f32 v[98:99], v[118:119], v[162:163]
	v_pk_add_f32 v[96:97], v[116:117], v[160:161]
	v_pk_add_f32 v[104:105], v[112:113], v[164:165]
	v_pk_add_f32 v[88:89], v[88:89], v[168:169]
	s_waitcnt vmcnt(12)
	v_pk_add_f32 v[82:83], v[82:83], v[174:175]
	s_waitcnt vmcnt(4)
	v_pk_add_f32 v[64:65], v[64:65], v[204:205]
	v_pk_add_f32 v[80:81], v[80:81], v[172:173]
	v_pk_add_f32 v[110:111], v[110:111], v[178:179]
	v_pk_add_f32 v[108:109], v[108:109], v[176:177]
	v_pk_add_f32 v[102:103], v[102:103], v[182:183]
	v_pk_add_f32 v[100:101], v[100:101], v[180:181]
	v_pk_add_f32 v[78:79], v[78:79], v[186:187]
	v_pk_add_f32 v[76:77], v[76:77], v[184:185]
	v_pk_add_f32 v[74:75], v[74:75], v[190:191]
	v_pk_add_f32 v[72:73], v[72:73], v[188:189]
	v_pk_add_f32 v[94:95], v[94:95], v[194:195]
	v_pk_add_f32 v[92:93], v[92:93], v[192:193]
	v_pk_add_f32 v[86:87], v[86:87], v[198:199]
	v_pk_add_f32 v[84:85], v[84:85], v[196:197]
	v_pk_add_f32 v[70:71], v[70:71], v[202:203]
	v_pk_add_f32 v[68:69], v[68:69], v[200:201]
	v_pk_add_f32 v[66:67], v[66:67], v[206:207]
	global_store_dwordx4 v[208:209], v[96:99], off
	global_store_dwordx4 v[208:209], v[104:107], off offset:16
	global_store_dwordx4 v[208:209], v[88:91], off offset:512
	global_store_dwordx4 v[208:209], v[80:83], off offset:528
	global_store_dwordx4 v[210:211], v[108:111], off
	global_store_dwordx4 v[210:211], v[100:103], off offset:16
	global_store_dwordx4 v[210:211], v[76:79], off offset:512
	global_store_dwordx4 v[210:211], v[72:75], off offset:528
	global_store_dwordx4 v[212:213], v[92:95], off
	global_store_dwordx4 v[212:213], v[84:87], off offset:16
	global_store_dwordx4 v[212:213], v[68:71], off offset:512
	global_store_dwordx4 v[212:213], v[64:67], off offset:528
	s_nop 1
	v_lshl_add_u64 v[64:65], v[140:141], 0, s[24:25]
	v_mov_b64_e32 v[66:67], v[64:65]
	global_load_dwordx4 v[68:71], v[64:65], off
	global_load_dwordx4 v[72:75], v[64:65], off offset:16
	global_load_dwordx4 v[76:79], v[64:65], off offset:512
	global_load_dwordx4 v[80:83], v[64:65], off offset:528
	v_add_co_u32_e32 v96, vcc, s94, v64
	v_addc_co_u32_e32 v97, vcc, 0, v65, vcc
	v_add_co_u32_e32 v112, vcc, s0, v64
	global_load_dwordx4 v[84:87], v[96:97], off
	global_load_dwordx4 v[88:91], v[96:97], off offset:16
	global_load_dwordx4 v[92:95], v[96:97], off offset:512
	s_nop 0
	global_load_dwordx4 v[96:99], v[96:97], off offset:528
	v_addc_co_u32_e32 v113, vcc, 0, v65, vcc
	v_add_co_u32_e32 v140, vcc, s1, v64
	global_load_dwordx4 v[100:103], v[112:113], off
	global_load_dwordx4 v[104:107], v[112:113], off offset:16
	global_load_dwordx4 v[108:111], v[112:113], off offset:512
	s_nop 0
	global_load_dwordx4 v[112:115], v[112:113], off offset:528
	v_addc_co_u32_e32 v141, vcc, 0, v65, vcc
	global_load_dwordx4 v[116:119], v[140:141], off
	global_load_dwordx4 v[120:123], v[140:141], off offset:16
	global_load_dwordx4 v[124:127], v[140:141], off offset:512
	global_load_dwordx4 v[144:147], v[140:141], off offset:528
	s_waitcnt vmcnt(15)
	v_pk_add_f32 v[62:63], v[62:63], v[70:71]
	v_add_co_u32_e32 v140, vcc, s94, v66
	v_pk_add_f32 v[60:61], v[60:61], v[68:69]
	s_nop 0
	v_addc_co_u32_e32 v141, vcc, 0, v67, vcc
	v_add_co_u32_e32 v148, vcc, s0, v66
	s_waitcnt vmcnt(12)
	v_pk_add_f32 v[34:35], v[34:35], v[82:83]
	s_nop 0
	v_addc_co_u32_e32 v149, vcc, 0, v67, vcc
	v_add_co_u32_e32 v150, vcc, s1, v66
	v_pk_add_f32 v[32:33], v[32:33], v[80:81]
	s_nop 0
	v_addc_co_u32_e32 v151, vcc, 0, v67, vcc
	v_pk_add_f32 v[58:59], v[58:59], v[74:75]
	v_pk_add_f32 v[56:57], v[56:57], v[72:73]
	v_pk_add_f32 v[42:43], v[42:43], v[78:79]
	v_pk_add_f32 v[40:41], v[40:41], v[76:77]
	global_store_dwordx4 v[66:67], v[60:63], off
	global_store_dwordx4 v[66:67], v[56:59], off offset:16
	global_store_dwordx4 v[66:67], v[40:43], off offset:512
	global_store_dwordx4 v[66:67], v[32:35], off offset:528
	s_andn2_b64 vcc, exec, s[2:3]
	s_mov_b64 s[2:3], -1
	s_waitcnt lgkmcnt(0)
	s_waitcnt vmcnt(15)
	v_pk_add_f32 v[34:35], v[54:55], v[86:87]
	v_pk_add_f32 v[32:33], v[52:53], v[84:85]
	s_waitcnt vmcnt(14)
	v_pk_add_f32 v[42:43], v[50:51], v[90:91]
	v_pk_add_f32 v[40:41], v[48:49], v[88:89]
	s_waitcnt vmcnt(13)
	v_pk_add_f32 v[26:27], v[26:27], v[94:95]
	v_pk_add_f32 v[24:25], v[24:25], v[92:93]
	s_waitcnt vmcnt(12)
	v_pk_add_f32 v[22:23], v[22:23], v[98:99]
	v_pk_add_f32 v[20:21], v[20:21], v[96:97]
	s_waitcnt vmcnt(11)
	v_pk_add_f32 v[46:47], v[46:47], v[102:103]
	v_pk_add_f32 v[44:45], v[44:45], v[100:101]
	s_waitcnt vmcnt(10)
	v_pk_add_f32 v[38:39], v[38:39], v[106:107]
	s_waitcnt vmcnt(4)
	v_pk_add_f32 v[2:3], v[2:3], v[146:147]
	v_pk_add_f32 v[0:1], v[0:1], v[144:145]
	v_pk_add_f32 v[36:37], v[36:37], v[104:105]
	v_pk_add_f32 v[18:19], v[18:19], v[110:111]
	v_pk_add_f32 v[16:17], v[16:17], v[108:109]
	v_pk_add_f32 v[14:15], v[14:15], v[114:115]
	v_pk_add_f32 v[12:13], v[12:13], v[112:113]
	v_pk_add_f32 v[30:31], v[30:31], v[118:119]
	v_pk_add_f32 v[28:29], v[28:29], v[116:117]
	v_pk_add_f32 v[10:11], v[10:11], v[122:123]
	global_store_dwordx4 v[140:141], v[32:35], off
	global_store_dwordx4 v[140:141], v[40:43], off offset:16
	global_store_dwordx4 v[140:141], v[24:27], off offset:512
	global_store_dwordx4 v[140:141], v[20:23], off offset:528
	global_store_dwordx4 v[148:149], v[44:47], off
	global_store_dwordx4 v[148:149], v[36:39], off offset:16
	global_store_dwordx4 v[148:149], v[16:19], off offset:512
	global_store_dwordx4 v[148:149], v[12:15], off offset:528
	global_store_dwordx4 v[150:151], v[28:31], off
	v_pk_add_f32 v[8:9], v[8:9], v[120:121]
	v_pk_add_f32 v[6:7], v[6:7], v[126:127]
	v_pk_add_f32 v[4:5], v[4:5], v[124:125]
	global_store_dwordx4 v[150:151], v[0:3], off offset:528
	global_store_dwordx4 v[150:151], v[8:11], off offset:16
	global_store_dwordx4 v[150:151], v[4:7], off offset:512
	v_lshl_add_u64 v[0:1], v[64:65], 0, s[24:25]
	v_lshl_add_u64 v[2:3], v[66:67], 0, s[24:25]
	s_cbranch_vccnz .LBB0_753
	s_andn2_b64 vcc, exec, s[8:9]
	s_cbranch_vccnz .LBB0_752
	s_barrier
	s_branch .LBB0_752
